# v20 + P1 epilogue tile stores with nt hint
# baseline (speedup 1.0000x reference)
;     __device__ __forceinline__ void operator()(const pg8::f32x4 (&acc)[2][2][4][2], const Unit& u, int wr, int wc, int fr, int fq) const {
;     ...
;         } else { const int col0 = (u.pn - 8) * BM + wc * 32 + 8 * fq;
; #pragma unroll
;             for (int ai = 0; ai < 2; ++ai)
; #pragma unroll
;                 for (int m = 0; m < 4; ++m) { float* rowp = FZ + (size_t)(row0 + ai * HALF + m * 16) * 512 + col0;
; #pragma unroll
;                     for (int bj = 0; bj < 2; ++bj)
; #pragma unroll
;                         for (int n = 0; n < 2; ++n) *(pg8::f32x4*)(rowp + bj * HALF + 4 * n) = acc[ai][bj][m][n]; }
.LBB0_140:
	v_lshl_add_u32 v150, s20, 8, v156
	s_cmp_gt_i32 s44, 1
	v_ashrrev_i32_e32 v151, 31, v150
	s_mov_b64 s[20:21], -1
	s_cbranch_scc0 .LBB0_147
	s_lshl_b32 s13, s44, 8
	s_cmp_gt_u32 s44, 7
	s_cbranch_scc0 .LBB0_143
	v_or_b32_e32 v166, 16, v150
	v_readlane_b32 s20, v238, 45
	v_ashrrev_i32_e32 v167, 31, v166
	v_add_u32_e32 v138, s13, v159
	v_lshlrev_b64 v[152:153], 11, v[150:151]
	v_readlane_b32 s21, v238, 46
	v_lshlrev_b64 v[166:167], 11, v[166:167]
	v_lshlrev_b64 v[164:165], 2, v[138:139]
	v_lshl_add_u64 v[152:153], s[20:21], 0, v[152:153]
	v_lshl_add_u64 v[166:167], s[20:21], 0, v[166:167]
	v_lshl_add_u64 v[152:153], v[152:153], 0, v[164:165]
	v_lshl_add_u64 v[166:167], v[166:167], 0, v[164:165]
	global_store_dwordx4 v[152:153], v[126:129], off nt
	global_store_dwordx4 v[152:153], v[122:125], off offset:16 nt
	global_store_dwordx4 v[152:153], v[118:121], off offset:512 nt
	global_store_dwordx4 v[152:153], v[110:113], off offset:528 nt
	global_store_dwordx4 v[166:167], v[114:117], off nt
	global_store_dwordx4 v[166:167], v[106:109], off offset:16 nt
	global_store_dwordx4 v[166:167], v[98:101], off offset:512 nt
	global_store_dwordx4 v[166:167], v[90:93], off offset:528 nt
	v_or_b32_e32 v166, 32, v150
	v_ashrrev_i32_e32 v167, 31, v166
	v_lshlrev_b64 v[166:167], 11, v[166:167]
	v_lshl_add_u64 v[166:167], s[20:21], 0, v[166:167]
	v_lshl_add_u64 v[166:167], v[166:167], 0, v[164:165]
	global_store_dwordx4 v[166:167], v[102:105], off nt
	global_store_dwordx4 v[166:167], v[94:97], off offset:16 nt
	global_store_dwordx4 v[166:167], v[82:85], off offset:512 nt
	global_store_dwordx4 v[166:167], v[74:77], off offset:528 nt
	v_or_b32_e32 v166, 48, v150
	v_ashrrev_i32_e32 v167, 31, v166
	v_lshlrev_b64 v[166:167], 11, v[166:167]
	v_lshl_add_u64 v[166:167], s[20:21], 0, v[166:167]
	s_mov_b32 s15, 0x40000
	v_lshl_add_u64 v[164:165], v[166:167], 0, v[164:165]
	v_add_co_u32_e32 v166, vcc, s15, v152
	s_mov_b64 s[20:21], 0x40000
	s_nop 0
	v_addc_co_u32_e32 v167, vcc, 0, v153, vcc
	s_mov_b32 s15, 0x48000
	global_store_dwordx4 v[164:165], v[86:89], off nt
	global_store_dwordx4 v[164:165], v[78:81], off offset:16 nt
	global_store_dwordx4 v[164:165], v[70:73], off offset:512 nt
	global_store_dwordx4 v[164:165], v[66:69], off offset:528 nt
	v_lshl_add_u64 v[164:165], v[152:153], 0, s[20:21]
	global_store_dwordx4 v[166:167], v[62:65], off nt
	global_store_dwordx4 v[164:165], v[58:61], off offset:16 nt
	global_store_dwordx4 v[164:165], v[50:53], off offset:512 nt
	global_store_dwordx4 v[164:165], v[42:45], off offset:528 nt
	v_add_co_u32_e32 v166, vcc, s15, v152
	s_mov_b64 s[20:21], 0x48000
	s_nop 0
	v_addc_co_u32_e32 v167, vcc, 0, v153, vcc
	s_mov_b32 s15, 0x50000
	v_lshl_add_u64 v[164:165], v[152:153], 0, s[20:21]
	global_store_dwordx4 v[166:167], v[54:57], off nt
	global_store_dwordx4 v[164:165], v[46:49], off offset:16 nt
	global_store_dwordx4 v[164:165], v[34:37], off offset:512 nt
	global_store_dwordx4 v[164:165], v[26:29], off offset:528 nt
	s_mov_b64 s[20:21], 0x50000
	v_add_co_u32_e32 v166, vcc, s15, v152
	v_lshl_add_u64 v[164:165], v[152:153], 0, s[20:21]
	s_nop 0
	v_addc_co_u32_e32 v167, vcc, 0, v153, vcc
	s_mov_b64 s[20:21], 0x58000
	global_store_dwordx4 v[166:167], v[38:41], off nt
	global_store_dwordx4 v[164:165], v[30:33], off offset:16 nt
	global_store_dwordx4 v[164:165], v[18:21], off offset:512 nt
	global_store_dwordx4 v[164:165], v[10:13], off offset:528 nt
	v_lshl_add_u64 v[164:165], v[152:153], 0, s[20:21]
	v_add_co_u32_e32 v152, vcc, 0x58000, v152
	s_mov_b64 s[20:21], 0
	s_nop 0
	v_addc_co_u32_e32 v153, vcc, 0, v153, vcc
	global_store_dwordx4 v[152:153], v[22:25], off nt
	global_store_dwordx4 v[164:165], v[14:17], off offset:16 nt
	global_store_dwordx4 v[164:165], v[6:9], off offset:512 nt
	global_store_dwordx4 v[164:165], v[2:5], off offset:528 nt
; __device__ __forceinline__ unsigned cvt_pk_bf16(float lo, float hi) { unsigned r; asm volatile("v_cvt_pk_bf16_f32 %0, %1, %2" : "=v"(r) : "v"(lo), "v"(hi)); return r; }
;     __device__ __forceinline__ void operator()(const pg8::f32x4 (&acc)[2][2][4][2], const Unit& u, int wr, int wc, int fr, int fq) const {
;     ...
;         } else if (u.pn < 8) { const int col0 = u.pn * BM + wc * 32 + 8 * fq;
; #pragma unroll
;             for (int ai = 0; ai < 2; ++ai)
; #pragma unroll
;                 for (int m = 0; m < 4; ++m) { bf16* rowp = PB + (size_t)(row0 + ai * HALF + m * 16) * PBW + col0;
; #pragma unroll
;                     for (int bj = 0; bj < 2; ++bj) { const pg8::f32x4 v0 = acc[ai][bj][m][0], v1 = acc[ai][bj][m][1]; u32x4 w; w.x = cvt_pk_bf16(v0[0], v0[1]); w.y = cvt_pk_bf16(v0[2], v0[3]); w.z = cvt_pk_bf16(v1[0], v1[1]); w.w = cvt_pk_bf16(v1[2], v1[3]);
;                         *(u32x4*)(rowp + bj * HALF) = w; } }
.LBB0_143:
	s_andn2_b64 vcc, exec, s[20:21]
	s_cbranch_vccnz .LBB0_145
	v_or_b32_e32 v138, s13, v158
	v_lshlrev_b64 v[152:153], 12, v[150:151]
	v_lshl_add_u64 v[152:153], s[56:57], 0, v[152:153]
	v_lshlrev_b32_e32 v138, 1, v138
	v_lshl_add_u64 v[152:153], v[152:153], 0, v[138:139]
	v_cvt_pk_bf16_f32 v164, v126, v127
	v_cvt_pk_bf16_f32 v165, v128, v129
	v_cvt_pk_bf16_f32 v166, v122, v123
	v_cvt_pk_bf16_f32 v167, v124, v125
	global_store_dwordx4 v[152:153], v[164:167], off nt
	s_mov_b32 s13, 0x80000
	v_add_co_u32_e32 v170, vcc, s13, v152
	v_cvt_pk_bf16_f32 v164, v118, v119
	v_cvt_pk_bf16_f32 v165, v120, v121
	v_cvt_pk_bf16_f32 v166, v110, v111
	v_cvt_pk_bf16_f32 v167, v112, v113
	global_store_dwordx4 v[152:153], v[164:167], off offset:256 nt
	s_mov_b64 s[20:21], 0x80000
	v_addc_co_u32_e32 v171, vcc, 0, v153, vcc
	v_or_b32_e32 v164, 16, v150
	v_ashrrev_i32_e32 v165, 31, v164
	v_lshlrev_b64 v[164:165], 12, v[164:165]
	v_lshl_add_u64 v[164:165], s[56:57], 0, v[164:165]
	v_lshl_add_u64 v[168:169], v[164:165], 0, v[138:139]
	v_cvt_pk_bf16_f32 v164, v114, v115
	v_cvt_pk_bf16_f32 v165, v116, v117
	v_cvt_pk_bf16_f32 v166, v106, v107
	v_cvt_pk_bf16_f32 v167, v108, v109
	global_store_dwordx4 v[168:169], v[164:167], off nt
	s_mov_b32 s13, 0x90000
	s_nop 0
	v_cvt_pk_bf16_f32 v164, v98, v99
	v_cvt_pk_bf16_f32 v165, v100, v101
	v_cvt_pk_bf16_f32 v166, v90, v91
	v_cvt_pk_bf16_f32 v167, v92, v93
	global_store_dwordx4 v[168:169], v[164:167], off offset:256 nt
	s_nop 1
	v_or_b32_e32 v164, 32, v150
	v_ashrrev_i32_e32 v165, 31, v164
	v_lshlrev_b64 v[164:165], 12, v[164:165]
	v_lshl_add_u64 v[164:165], s[56:57], 0, v[164:165]
	v_lshl_add_u64 v[168:169], v[164:165], 0, v[138:139]
	v_cvt_pk_bf16_f32 v164, v102, v103
	v_cvt_pk_bf16_f32 v165, v104, v105
	v_cvt_pk_bf16_f32 v166, v94, v95
	v_cvt_pk_bf16_f32 v167, v96, v97
	global_store_dwordx4 v[168:169], v[164:167], off nt
	s_nop 1
	v_cvt_pk_bf16_f32 v164, v82, v83
	v_cvt_pk_bf16_f32 v165, v84, v85
	v_cvt_pk_bf16_f32 v166, v74, v75
	v_cvt_pk_bf16_f32 v167, v76, v77
	global_store_dwordx4 v[168:169], v[164:167], off offset:256 nt
	s_nop 1
	v_or_b32_e32 v164, 48, v150
	v_ashrrev_i32_e32 v165, 31, v164
	v_lshlrev_b64 v[164:165], 12, v[164:165]
	v_lshl_add_u64 v[164:165], s[56:57], 0, v[164:165]
	v_lshl_add_u64 v[168:169], v[164:165], 0, v[138:139]
	v_cvt_pk_bf16_f32 v164, v86, v87
	v_cvt_pk_bf16_f32 v165, v88, v89
	v_cvt_pk_bf16_f32 v166, v78, v79
	v_cvt_pk_bf16_f32 v167, v80, v81
	global_store_dwordx4 v[168:169], v[164:167], off nt
	s_nop 1
	v_cvt_pk_bf16_f32 v164, v70, v71
	v_cvt_pk_bf16_f32 v165, v72, v73
	v_cvt_pk_bf16_f32 v166, v66, v67
	v_cvt_pk_bf16_f32 v167, v68, v69
	global_store_dwordx4 v[168:169], v[164:167], off offset:256 nt
	v_lshl_add_u64 v[168:169], v[152:153], 0, s[20:21]
	s_mov_b64 s[20:21], 0x90000
	v_cvt_pk_bf16_f32 v164, v62, v63
	v_cvt_pk_bf16_f32 v165, v64, v65
	v_cvt_pk_bf16_f32 v166, v58, v59
	v_cvt_pk_bf16_f32 v167, v60, v61
	global_store_dwordx4 v[170:171], v[164:167], off nt
	v_add_co_u32_e32 v170, vcc, s13, v152
	s_nop 0
	v_cvt_pk_bf16_f32 v164, v50, v51
	v_cvt_pk_bf16_f32 v165, v52, v53
	v_cvt_pk_bf16_f32 v166, v42, v43
	v_cvt_pk_bf16_f32 v167, v44, v45
	global_store_dwordx4 v[168:169], v[164:167], off offset:256 nt
	v_addc_co_u32_e32 v171, vcc, 0, v153, vcc
	s_nop 0
	v_cvt_pk_bf16_f32 v164, v54, v55
	v_cvt_pk_bf16_f32 v165, v56, v57
	v_cvt_pk_bf16_f32 v166, v46, v47
	v_cvt_pk_bf16_f32 v167, v48, v49
	s_mov_b32 s13, 0xa0000
	v_lshl_add_u64 v[168:169], v[152:153], 0, s[20:21]
	global_store_dwordx4 v[170:171], v[164:167], off nt
	s_mov_b64 s[20:21], 0xa0000
	v_add_co_u32_e32 v170, vcc, s13, v152
	v_cvt_pk_bf16_f32 v164, v34, v35
	v_cvt_pk_bf16_f32 v165, v36, v37
	v_cvt_pk_bf16_f32 v166, v26, v27
	v_cvt_pk_bf16_f32 v167, v28, v29
	global_store_dwordx4 v[168:169], v[164:167], off offset:256 nt
	v_lshl_add_u64 v[168:169], v[152:153], 0, s[20:21]
	v_addc_co_u32_e32 v171, vcc, 0, v153, vcc
	v_cvt_pk_bf16_f32 v164, v38, v39
	v_cvt_pk_bf16_f32 v165, v40, v41
	v_cvt_pk_bf16_f32 v166, v30, v31
	v_cvt_pk_bf16_f32 v167, v32, v33
	s_mov_b64 s[20:21], 0xb0000
	s_mov_b32 s13, 0xb0000
	global_store_dwordx4 v[170:171], v[164:167], off nt
	s_nop 1
	v_cvt_pk_bf16_f32 v164, v18, v19
	v_cvt_pk_bf16_f32 v165, v20, v21
	v_cvt_pk_bf16_f32 v166, v10, v11
	v_cvt_pk_bf16_f32 v167, v12, v13
	global_store_dwordx4 v[168:169], v[164:167], off offset:256 nt
	v_lshl_add_u64 v[168:169], v[152:153], 0, s[20:21]
	v_add_co_u32_e32 v152, vcc, s13, v152
	v_cvt_pk_bf16_f32 v164, v22, v23
	v_cvt_pk_bf16_f32 v165, v24, v25
	v_cvt_pk_bf16_f32 v166, v14, v15
	v_cvt_pk_bf16_f32 v167, v16, v17
	s_nop 1
	v_addc_co_u32_e32 v153, vcc, 0, v153, vcc
	global_store_dwordx4 v[152:153], v[164:167], off nt
	s_nop 1
	v_cvt_pk_bf16_f32 v164, v6, v7
	v_cvt_pk_bf16_f32 v165, v8, v9
	v_cvt_pk_bf16_f32 v166, v2, v3
	v_cvt_pk_bf16_f32 v167, v4, v5
	global_store_dwordx4 v[168:169], v[164:167], off offset:256 nt

; __device__ __forceinline__ unsigned cvt_pk_bf16(float lo, float hi) { unsigned r; asm volatile("v_cvt_pk_bf16_f32 %0, %1, %2" : "=v"(r) : "v"(lo), "v"(hi)); return r; }
;     __device__ __forceinline__ void operator()(const pg8::f32x4 (&acc)[2][2][4][2], const Unit& u, int wr, int wc, int fr, int fq) const {
;     ...
;         if (u.pn < 2) { const int col0 = u.pn * BM + wc * 32 + 8 * fq;
; #pragma unroll
;             for (int ai = 0; ai < 2; ++ai)
; #pragma unroll
;                 for (int m = 0; m < 4; ++m) { const size_t r = (size_t)(row0 + ai * HALF + m * 16);
; #pragma unroll
;                     for (int bj = 0; bj < 2; ++bj) { const int col = col0 + bj * HALF; const pg8::f32x4 v0 = acc[ai][bj][m][0], v1 = acc[ai][bj][m][1]; u32x4 w; w.x = cvt_pk_bf16(v0[0], v0[1]); w.y = cvt_pk_bf16(v0[2], v0[3]); w.z = cvt_pk_bf16(v1[0], v1[1]); w.w = cvt_pk_bf16(v1[2], v1[3]);
;                         *(u32x4*)(U5 + ((size_t)(col >> 4) * MTOK + r) * 16 + (col & 15)) = w; } }
.LBB0_148:
	v_lshl_or_b32 v138, s44, 8, v158
	v_cvt_pk_bf16_f32 v126, v126, v127
	v_cvt_pk_bf16_f32 v127, v128, v129
	v_cvt_pk_bf16_f32 v128, v122, v123
	v_cvt_pk_bf16_f32 v129, v124, v125
	v_ashrrev_i32_e32 v124, 4, v138
	v_mad_i64_i32 v[122:123], s[20:21], v124, s43, v[150:151]
	v_lshlrev_b64 v[122:123], 5, v[122:123]
	v_lshl_add_u64 v[122:123], v[140:141], 0, v[122:123]
	global_store_dwordx4 v[122:123], v[126:129], off nt
	v_or_b32_e32 v122, 8, v124
	v_cvt_pk_bf16_f32 v118, v118, v119
	v_cvt_pk_bf16_f32 v119, v120, v121
	v_cvt_pk_bf16_f32 v120, v110, v111
	v_mad_i64_i32 v[110:111], s[20:21], v122, s43, v[150:151]
	v_lshlrev_b64 v[110:111], 5, v[110:111]
	v_lshl_add_u64 v[110:111], v[140:141], 0, v[110:111]
	v_cvt_pk_bf16_f32 v121, v112, v113
	global_store_dwordx4 v[110:111], v[118:121], off nt
	v_cvt_pk_bf16_f32 v110, v114, v115
	v_cvt_pk_bf16_f32 v111, v116, v117
	v_cvt_pk_bf16_f32 v112, v106, v107
	v_cvt_pk_bf16_f32 v113, v108, v109
	s_nop 1
	v_or_b32_e32 v118, 16, v150
	v_ashrrev_i32_e32 v119, 31, v118
	v_mad_i64_i32 v[106:107], s[20:21], v124, s43, v[118:119]
	v_lshlrev_b64 v[106:107], 5, v[106:107]
	v_lshl_add_u64 v[106:107], v[140:141], 0, v[106:107]
	global_store_dwordx4 v[106:107], v[110:113], off nt
	v_cvt_pk_bf16_f32 v98, v98, v99
	v_cvt_pk_bf16_f32 v99, v100, v101
	v_cvt_pk_bf16_f32 v100, v90, v91
	v_mad_i64_i32 v[90:91], s[20:21], v122, s43, v[118:119]
	v_lshlrev_b64 v[90:91], 5, v[90:91]
	v_lshl_add_u64 v[90:91], v[140:141], 0, v[90:91]
	v_cvt_pk_bf16_f32 v101, v92, v93
	global_store_dwordx4 v[90:91], v[98:101], off nt
	v_cvt_pk_bf16_f32 v90, v102, v103
	v_cvt_pk_bf16_f32 v91, v104, v105
	v_cvt_pk_bf16_f32 v92, v94, v95
	v_cvt_pk_bf16_f32 v93, v96, v97
	s_nop 1
	v_or_b32_e32 v98, 32, v150
	v_ashrrev_i32_e32 v99, 31, v98
	v_mad_i64_i32 v[94:95], s[20:21], v124, s43, v[98:99]
	v_lshlrev_b64 v[94:95], 5, v[94:95]
	v_lshl_add_u64 v[94:95], v[140:141], 0, v[94:95]
	global_store_dwordx4 v[94:95], v[90:93], off nt
	v_cvt_pk_bf16_f32 v82, v82, v83
	v_cvt_pk_bf16_f32 v83, v84, v85
	v_cvt_pk_bf16_f32 v84, v74, v75
	v_mad_i64_i32 v[74:75], s[20:21], v122, s43, v[98:99]
	v_lshlrev_b64 v[74:75], 5, v[74:75]
	v_lshl_add_u64 v[74:75], v[140:141], 0, v[74:75]
	v_cvt_pk_bf16_f32 v85, v76, v77
	global_store_dwordx4 v[74:75], v[82:85], off nt
	v_cvt_pk_bf16_f32 v74, v86, v87
	v_cvt_pk_bf16_f32 v75, v88, v89
	v_cvt_pk_bf16_f32 v76, v78, v79
	v_cvt_pk_bf16_f32 v77, v80, v81
	s_nop 1
	v_or_b32_e32 v82, 48, v150
	v_ashrrev_i32_e32 v83, 31, v82
	v_mad_i64_i32 v[78:79], s[20:21], v124, s43, v[82:83]
	v_lshlrev_b64 v[78:79], 5, v[78:79]
	v_lshl_add_u64 v[78:79], v[140:141], 0, v[78:79]
	global_store_dwordx4 v[78:79], v[74:77], off nt
	v_cvt_pk_bf16_f32 v70, v70, v71
	v_cvt_pk_bf16_f32 v71, v72, v73
	v_cvt_pk_bf16_f32 v72, v66, v67
	v_mad_i64_i32 v[66:67], s[20:21], v122, s43, v[82:83]
	v_lshlrev_b64 v[66:67], 5, v[66:67]
	v_lshl_add_u64 v[66:67], v[140:141], 0, v[66:67]
	v_cvt_pk_bf16_f32 v73, v68, v69
	global_store_dwordx4 v[66:67], v[70:73], off nt
	v_add_u32_e32 v66, 0x80, v150
	v_ashrrev_i32_e32 v67, 31, v66
	v_cvt_pk_bf16_f32 v62, v62, v63
	v_cvt_pk_bf16_f32 v63, v64, v65
	v_cvt_pk_bf16_f32 v64, v58, v59
	v_mad_i64_i32 v[58:59], s[20:21], v124, s43, v[66:67]
	v_lshlrev_b64 v[58:59], 5, v[58:59]
	v_lshl_add_u64 v[58:59], v[140:141], 0, v[58:59]
	v_cvt_pk_bf16_f32 v65, v60, v61
	global_store_dwordx4 v[58:59], v[62:65], off nt
	v_cvt_pk_bf16_f32 v50, v50, v51
	v_cvt_pk_bf16_f32 v51, v52, v53
	v_cvt_pk_bf16_f32 v52, v42, v43
	v_mad_i64_i32 v[42:43], s[20:21], v122, s43, v[66:67]
	v_lshlrev_b64 v[42:43], 5, v[42:43]
	v_lshl_add_u64 v[42:43], v[140:141], 0, v[42:43]
	v_cvt_pk_bf16_f32 v53, v44, v45
	global_store_dwordx4 v[42:43], v[50:53], off nt
	v_cvt_pk_bf16_f32 v42, v54, v55
	v_cvt_pk_bf16_f32 v43, v56, v57
	v_cvt_pk_bf16_f32 v44, v46, v47
	v_cvt_pk_bf16_f32 v45, v48, v49
	s_nop 1
	v_add_u32_e32 v50, 0x90, v150
	v_ashrrev_i32_e32 v51, 31, v50
	v_mad_i64_i32 v[46:47], s[20:21], v124, s43, v[50:51]
	v_lshlrev_b64 v[46:47], 5, v[46:47]
	v_lshl_add_u64 v[46:47], v[140:141], 0, v[46:47]
	global_store_dwordx4 v[46:47], v[42:45], off nt
	v_cvt_pk_bf16_f32 v34, v34, v35
	v_cvt_pk_bf16_f32 v35, v36, v37
	v_cvt_pk_bf16_f32 v36, v26, v27
	v_mad_i64_i32 v[26:27], s[20:21], v122, s43, v[50:51]
	v_lshlrev_b64 v[26:27], 5, v[26:27]
	v_lshl_add_u64 v[26:27], v[140:141], 0, v[26:27]
	v_cvt_pk_bf16_f32 v37, v28, v29
	global_store_dwordx4 v[26:27], v[34:37], off nt
	v_cvt_pk_bf16_f32 v26, v38, v39
	v_cvt_pk_bf16_f32 v27, v40, v41
	v_cvt_pk_bf16_f32 v28, v30, v31
	v_cvt_pk_bf16_f32 v29, v32, v33
	s_nop 1
	v_add_u32_e32 v34, 0xa0, v150
	v_ashrrev_i32_e32 v35, 31, v34
	v_mad_i64_i32 v[30:31], s[20:21], v124, s43, v[34:35]
	v_lshlrev_b64 v[30:31], 5, v[30:31]
	v_lshl_add_u64 v[30:31], v[140:141], 0, v[30:31]
	global_store_dwordx4 v[30:31], v[26:29], off nt
	v_cvt_pk_bf16_f32 v18, v18, v19
	v_cvt_pk_bf16_f32 v19, v20, v21
	v_cvt_pk_bf16_f32 v20, v10, v11
	v_mad_i64_i32 v[10:11], s[20:21], v122, s43, v[34:35]
	v_lshlrev_b64 v[10:11], 5, v[10:11]
	v_lshl_add_u64 v[10:11], v[140:141], 0, v[10:11]
	v_cvt_pk_bf16_f32 v21, v12, v13
	global_store_dwordx4 v[10:11], v[18:21], off nt
	v_cvt_pk_bf16_f32 v10, v22, v23
	v_cvt_pk_bf16_f32 v11, v24, v25
	v_cvt_pk_bf16_f32 v12, v14, v15
	v_cvt_pk_bf16_f32 v13, v16, v17
	s_nop 1
	v_add_u32_e32 v18, 0xb0, v150
	v_ashrrev_i32_e32 v19, 31, v18
	v_mad_i64_i32 v[14:15], s[20:21], v124, s43, v[18:19]
	v_lshlrev_b64 v[14:15], 5, v[14:15]
	v_lshl_add_u64 v[14:15], v[140:141], 0, v[14:15]
	global_store_dwordx4 v[14:15], v[10:13], off nt
	v_cvt_pk_bf16_f32 v6, v6, v7
	v_cvt_pk_bf16_f32 v7, v8, v9
	v_cvt_pk_bf16_f32 v8, v2, v3
	v_mad_i64_i32 v[2:3], s[20:21], v122, s43, v[18:19]
	v_lshlrev_b64 v[2:3], 5, v[2:3]
	v_lshl_add_u64 v[2:3], v[140:141], 0, v[2:3]
	v_cvt_pk_bf16_f32 v9, v4, v5
	global_store_dwordx4 v[2:3], v[6:9], off nt
	s_andn2_b64 vcc, exec, s[0:1]
	s_mov_b64 s[0:1], -1
	s_cbranch_vccnz .LBB0_133
